# GEMM/attention unit-loop headers: gridDim.x read from the spill VGPR lane (v_readlane) instead of a per-tile s_load + wait
# speedup vs baseline: 1.0125x; 1.0005x over previous
;     __host__ __device__ bool next(int i, Unit& u) const { const bool ok = StaticOrder::next(i >> 1, u); u.z = i & 1; return ok; }
;     __host__ __device__ bool next(int i, Unit& u) const {
;         const long L = (long)i * G + c; if (L >= nwg) return false;
;         int wgid = (int)L; { const int q = nwg / NXCD, r = nwg % NXCD, xcd = wgid % NXCD, off = wgid / NXCD; wgid = (xcd < r ? xcd * (q + 1) : r * (q + 1) + (xcd - r) * q) + off; }
;         const int nig = WGM * nN, gid = wgid / nig, fm = gid * WGM, gsz = (nM - fm) < WGM ? (nM - fm) : WGM;
;         u.pm = fm + ((wgid % nig) % gsz); u.pn = (wgid % nig) / gsz; u.z = 0; return true;
; template <class Epi, class Sched, bool ALIGN_EPI = true, bool SP2 = true>
; __device__ __forceinline__ void gemm_phase(LAS unsigned char* lds, const Gemm g, const Sched& S, const Epi& E) {
;     ...
;         const bool has_next = S.next(ui + 1, nxt);
.LBB0_135:
	v_readlane_b32 s30, v254, 13
	v_readlane_b32 s31, v254, 14
	v_readlane_b32 s5, v254, 2
	s_add_i32 s63, s63, 1
	s_mul_i32 s2, s63, s56
	s_waitcnt lgkmcnt(0)
	s_mul_hi_u32 s3, s63, s5
	s_add_i32 s3, s3, s2
	s_mul_i32 s2, s63, s5
	s_add_u32 s30, s2, s74
	s_addc_u32 s31, s3, s57
	v_cmp_gt_i64_e32 vcc, s[30:31], v[158:159]
	v_cmp_lt_i64_e64 s[2:3], s[30:31], v[156:157]
	s_cbranch_vccnz .LBB0_137
	s_ashr_i32 s5, s30, 31
	s_lshr_b32 s5, s5, 29
	s_add_i32 s5, s30, s5
	s_ashr_i32 s18, s5, 3
	s_and_b32 s5, s5, -8
	s_sub_i32 s5, s30, s5
	s_cmp_lt_i32 s5, 0
	s_cselect_b32 s26, s59, 0x1f8
	s_mul_i32 s5, s5, s26
	s_add_i32 s5, s5, s18
	s_mul_hi_i32 s18, s5, 0x82082083
	s_add_i32 s18, s18, s5
	s_lshr_b32 s26, s18, 31
	s_ashr_i32 s18, s18, 8
	s_add_i32 s18, s18, s26
	s_lshl_b32 s27, s18, 3
	s_sub_i32 s26, 64, s27
	s_min_i32 s28, s26, 8
	s_abs_i32 s26, s28
	v_cvt_f32_u32_e32 v2, s26
	s_sub_i32 s30, 0, s26
	s_mulk_i32 s18, 0x1f8
	s_sub_i32 s5, s5, s18
	v_rcp_iflag_f32_e32 v2, v2
	s_abs_i32 s18, s5
	s_xor_b32 s29, s5, s28
	s_ashr_i32 s29, s29, 31
	v_mul_f32_e32 v2, 0x4f7ffffe, v2
	v_cvt_u32_f32_e32 v2, v2
	s_nop 0
	v_readfirstlane_b32 s31, v2
	s_mul_i32 s30, s30, s31
	s_mul_hi_u32 s30, s31, s30
	s_add_i32 s31, s31, s30
	s_mul_hi_u32 s30, s18, s31
	s_mul_i32 s31, s30, s26
	s_sub_i32 s18, s18, s31
	s_add_i32 s34, s30, 1
	s_sub_i32 s31, s18, s26
	s_cmp_ge_u32 s18, s26
	s_cselect_b32 s30, s34, s30
	s_cselect_b32 s18, s31, s18
	s_add_i32 s31, s30, 1
	s_cmp_ge_u32 s18, s26
	s_cselect_b32 s18, s31, s30
	s_xor_b32 s18, s18, s29
	s_sub_i32 s26, s18, s29
	s_mul_i32 s18, s26, s28
	s_sub_i32 s5, s5, s18
	s_add_i32 s28, s27, s5

;     __host__ __device__ bool next(int i, Unit& u) const { const bool ok = StaticOrder::next(i >> 1, u); u.z = i & 1; return ok; }
;     __host__ __device__ bool next(int i, Unit& u) const {
;         const long L = (long)i * G + c; if (L >= nwg) return false;
;         int wgid = (int)L; { const int q = nwg / NXCD, r = nwg % NXCD, xcd = wgid % NXCD, off = wgid / NXCD; wgid = (xcd < r ? xcd * (q + 1) : r * (q + 1) + (xcd - r) * q) + off; }
;         const int nig = WGM * nN, gid = wgid / nig, fm = gid * WGM, gsz = (nM - fm) < WGM ? (nM - fm) : WGM;
;         u.pm = fm + ((wgid % nig) % gsz); u.pn = (wgid % nig) / gsz; u.z = 0; return true;
.LBB0_444:
	v_readlane_b32 s11, v254, 2
	s_add_i32 s36, s36, 1
	s_mul_i32 s0, s36, s41
	s_waitcnt lgkmcnt(0)
	s_mul_hi_u32 s1, s36, s11
	s_add_i32 s1, s1, s0
	s_mul_i32 s0, s36, s11
	s_add_u32 s14, s0, s74
	s_addc_u32 s15, s1, s26
	v_cmp_gt_i64_e32 vcc, s[14:15], v[144:145]
	v_cmp_lt_i64_e64 s[0:1], s[14:15], v[142:143]
	s_cbranch_vccnz .LBB0_450
	s_ashr_i32 s10, s14, 31
	s_lshr_b32 s10, s10, 29
	s_add_i32 s12, s14, s10
	s_and_b32 s10, s12, -8
	s_sub_i32 s13, s14, s10
	s_cmp_gt_i32 s13, -1
	s_mov_b64 s[10:11], -1
	s_cbranch_scc0 .LBB0_447
	s_lshl_b32 s14, s13, 7
	s_mov_b64 s[10:11], 0

; #define mkref(L) fox_ref((L), RD, biasK, thr, F.lane)
; #define mkref(L) dsa_ref((L), RA, KVA, SELM)
; __global__ void __launch_bounds__(NWAVES * 64, 2) mk_fwd(Args args) {
;     ...
;                 for (int j = 0; j < NR; ++j) { const fa::Ref nxt = (j + 1 < NR) ? mkref(snake(j + 1, (int)blockIdx.x, F.G)) : cur;
.LBB0_1217:
	s_add_i32 s42, s6, 1
	s_cmp_ge_i32 s42, s30
	s_mov_b32 s43, s20
	s_cbranch_scc1 .LBB0_1219
	v_readlane_b32 s5, v254, 2
	s_bitcmp0_b32 s6, 0
	s_cselect_b32 s4, s9, s74
	s_waitcnt lgkmcnt(0)
	s_mul_i32 s5, s42, s5
	s_add_i32 s4, s4, s5
	s_ashr_i32 s6, s4, 4
	s_lshl_b32 s5, s4, 5
	s_and_b32 s5, s5, 32
	s_lshl_b32 s10, s6, 6
	s_sub_i32 s5, s5, s10
	s_bfe_u32 s12, s4, 0x10001
	s_addk_i32 s5, 0xfc0
	s_lshl_b32 s4, s4, 10
	s_and_b32 s13, s4, 0x3000
	s_ashr_i32 s4, s5, 31
	s_add_u32 s16, s5, s13
	s_addc_u32 s17, s4, 0
	s_lshl_b64 s[10:11], s[16:17], 12
	s_add_u32 s4, s31, s10
	s_addc_u32 s5, s33, s11
	s_lshl_b32 s14, s12, 11
	s_add_u32 s4, s4, s14
	s_addc_u32 s5, s5, 0
	s_add_u32 s10, s37, s10
	s_addc_u32 s11, s38, s11
	s_add_u32 s10, s10, s14
	s_addc_u32 s11, s11, 0
	s_lshl_b32 s13, s13, 10
	s_add_u32 s13, s34, s13
	s_addc_u32 s14, s35, 0
	s_lshl_b32 s12, s12, 8
	s_add_u32 s12, s13, s12
	s_addc_u32 s13, s14, 0
	s_add_u32 s14, s12, 0x200
	s_addc_u32 s15, s13, 0
	s_lshl_b64 s[16:17], s[16:17], 9
	s_add_u32 s16, s39, s16
	s_addc_u32 s17, s40, s17
	s_sub_i32 s43, 64, s6

;     __host__ __device__ bool next(int i, Unit& u) const {
;         const long L = (long)i * G + c; if (L >= nwg) return false;
;         int wgid = (int)L; { const int q = nwg / NXCD, r = nwg % NXCD, xcd = wgid % NXCD, off = wgid / NXCD; wgid = (xcd < r ? xcd * (q + 1) : r * (q + 1) + (xcd - r) * q) + off; }
;         const int nig = WGM * nN, gid = wgid / nig, fm = gid * WGM, gsz = (nM - fm) < WGM ? (nM - fm) : WGM;
;         u.pm = fm + ((wgid % nig) % gsz); u.pn = (wgid % nig) / gsz; u.z = 0; return true;
;     __host__ __device__ bool next(int i, Unit& u) const { const bool ok = StaticOrder::next(i >> 1, u); u.z = i & 1; return ok; }
.LBB0_1453:
	v_readlane_b32 s26, v254, 13
	v_readlane_b32 s27, v254, 14
	v_readlane_b32 s23, v254, 2
	s_add_i32 s59, s59, 1
	s_lshr_b32 s0, s59, 1
	s_waitcnt lgkmcnt(0)
	s_mul_hi_i32 s1, s0, s23
	s_mul_i32 s0, s0, s23
	s_add_u32 s26, s0, s74
	s_addc_u32 s27, s1, s56
	v_cmp_gt_i64_e32 vcc, s[26:27], v[208:209]
	v_cmp_lt_i64_e64 s[0:1], s[26:27], v[206:207]
	s_cbranch_vccnz .LBB0_1459
	s_ashr_i32 s22, s26, 31
	s_lshr_b32 s22, s22, 29
	s_add_i32 s24, s26, s22
	s_and_b32 s22, s24, -8
	s_sub_i32 s25, s26, s22
	s_cmp_gt_i32 s25, -1
	s_mov_b64 s[22:23], -1
	s_cbranch_scc0 .LBB0_1456
	s_lshl_b32 s26, s25, 7
	s_mov_b64 s[22:23], 0

;     __host__ __device__ bool next(int i, Unit& u) const { const bool ok = StaticOrder::next(i >> 1, u); u.z = i & 1; return ok; }
;     __host__ __device__ bool next(int i, Unit& u) const {
;         const long L = (long)i * G + c; if (L >= nwg) return false;
;         int wgid = (int)L; { const int q = nwg / NXCD, r = nwg % NXCD, xcd = wgid % NXCD, off = wgid / NXCD; wgid = (xcd < r ? xcd * (q + 1) : r * (q + 1) + (xcd - r) * q) + off; }
;         const int nig = WGM * nN, gid = wgid / nig, fm = gid * WGM, gsz = (nM - fm) < WGM ? (nM - fm) : WGM;
;         u.pm = fm + ((wgid % nig) % gsz); u.pn = (wgid % nig) / gsz; u.z = 0; return true;
.LBB0_1632:
	v_readlane_b32 s41, v254, 2
	s_add_i32 s61, s61, 1
	s_mul_i32 s2, s61, s64
	s_waitcnt lgkmcnt(0)
	s_mul_hi_u32 s3, s61, s41
	s_add_i32 s3, s3, s2
	s_mul_i32 s2, s61, s41
	s_add_u32 s44, s2, s74
	s_addc_u32 s45, s3, s65
	v_cmp_gt_i64_e32 vcc, s[44:45], v[192:193]
	v_cmp_lt_i64_e64 s[2:3], s[44:45], v[190:191]
	s_cbranch_vccnz .LBB0_1638
	s_ashr_i32 s40, s44, 31
	s_lshr_b32 s40, s40, 29
	s_add_i32 s42, s44, s40
	s_and_b32 s40, s42, -8
	s_sub_i32 s43, s44, s40
	s_cmp_gt_i32 s43, -1
	s_mov_b64 s[40:41], -1
	s_cbranch_scc0 .LBB0_1635
	s_lshl_b32 s44, s43, 7
	s_mov_b64 s[40:41], 0

;     __host__ __device__ bool next(int i, Unit& u) const { const bool ok = StaticOrder::next(i >> 1, u); u.z = i & 1; return ok; }
;     __host__ __device__ bool next(int i, Unit& u) const {
;         const long L = (long)i * G + c; if (L >= nwg) return false;
;         int wgid = (int)L; { const int q = nwg / NXCD, r = nwg % NXCD, xcd = wgid % NXCD, off = wgid / NXCD; wgid = (xcd < r ? xcd * (q + 1) : r * (q + 1) + (xcd - r) * q) + off; }
;         const int nig = WGM * nN, gid = wgid / nig, fm = gid * WGM, gsz = (nM - fm) < WGM ? (nM - fm) : WGM;
;         u.pm = fm + ((wgid % nig) % gsz); u.pn = (wgid % nig) / gsz; u.z = 0; return true;
;     __device__ __forceinline__ void operator()(const f32x4 (&acc)[2][2][4][2], const Unit& u, int wr, int wc, int fr, int fq) const {
;     ...
;         for (int ai = 0; ai < 2; ++ai)
; #pragma unroll
;             for (int m = 0; m < 4; ++m) sq[ai][m] = ss[u.pm * BM + ai * HALF + wr * 64 + m * 16 + fr];
.LBB0_1807:
	v_readlane_b32 s23, v254, 2
	v_lshl_add_u32 v233, s2, 8, v166
	v_lshlrev_b32_e32 v233, 2, v233
	global_load_dword v234, v233, s[16:17]
	global_load_dword v235, v233, s[16:17] offset:64
	global_load_dword v236, v233, s[16:17] offset:128
	global_load_dword v237, v233, s[16:17] offset:192
	global_load_dword v238, v233, s[16:17] offset:512
	global_load_dword v239, v233, s[16:17] offset:576
	global_load_dword v240, v233, s[16:17] offset:640
	global_load_dword v241, v233, s[16:17] offset:704
	s_add_i32 s44, s44, 1
	s_mul_i32 s0, s44, s47
	s_waitcnt lgkmcnt(0)
	s_mul_hi_u32 s1, s44, s23
	s_add_i32 s1, s1, s0
	s_mul_i32 s0, s44, s23
	s_add_u32 s26, s0, s74
	s_addc_u32 s27, s1, s38
	v_cmp_gt_i64_e32 vcc, s[26:27], v[146:147]
	v_cmp_lt_i64_e64 s[0:1], s[26:27], v[144:145]
	s_cbranch_vccnz .LBB0_1809
	s_ashr_i32 s22, s26, 31
	s_lshr_b32 s22, s22, 29
	s_add_i32 s22, s26, s22
	s_ashr_i32 s23, s22, 3
	s_and_b32 s22, s22, -8
	s_sub_i32 s22, s26, s22
	s_cmp_lt_i32 s22, 0
	s_cselect_b32 s24, s39, 0x2b0
	s_mul_i32 s22, s22, s24
	s_add_i32 s22, s22, s23
	s_mul_hi_i32 s23, s22, 0x2fa0be83
	s_lshr_b32 s24, s23, 31
	s_ashr_i32 s23, s23, 7
	s_add_i32 s23, s23, s24
	s_lshl_b32 s24, s23, 3
	s_sub_i32 s25, 64, s24
	s_min_i32 s25, s25, 8
	s_abs_i32 s26, s25
	v_cvt_f32_u32_e32 v2, s26
	s_sub_i32 s28, 0, s26
	s_mulk_i32 s23, 0x2b0
	s_sub_i32 s23, s22, s23
	v_rcp_iflag_f32_e32 v2, v2
	s_abs_i32 s22, s23
	s_xor_b32 s27, s23, s25
	s_ashr_i32 s27, s27, 31
	v_mul_f32_e32 v2, 0x4f7ffffe, v2
	v_cvt_u32_f32_e32 v2, v2
	s_nop 0
	v_readfirstlane_b32 s29, v2
	s_mul_i32 s28, s28, s29
	s_mul_hi_u32 s28, s29, s28
	s_add_i32 s29, s29, s28
	s_mul_hi_u32 s28, s22, s29
	s_mul_i32 s29, s28, s26
	s_sub_i32 s22, s22, s29
	s_add_i32 s34, s28, 1
	s_sub_i32 s29, s22, s26
	s_cmp_ge_u32 s22, s26
	s_cselect_b32 s28, s34, s28
	s_cselect_b32 s22, s29, s22
	s_add_i32 s29, s28, 1
	s_cmp_ge_u32 s22, s26
	s_cselect_b32 s22, s29, s28
	s_xor_b32 s22, s22, s27
	s_sub_i32 s22, s22, s27
	s_mul_i32 s25, s22, s25
	s_sub_i32 s23, s23, s25
	s_add_i32 s24, s24, s23

;     __host__ __device__ bool next(int i, Unit& u) const { const bool ok = StaticOrder::next(i >> 1, u); u.z = i & 1; return ok; }
;     __host__ __device__ bool next(int i, Unit& u) const {
;         const long L = (long)i * G + c; if (L >= nwg) return false;
;         int wgid = (int)L; { const int q = nwg / NXCD, r = nwg % NXCD, xcd = wgid % NXCD, off = wgid / NXCD; wgid = (xcd < r ? xcd * (q + 1) : r * (q + 1) + (xcd - r) * q) + off; }
;         const int nig = WGM * nN, gid = wgid / nig, fm = gid * WGM, gsz = (nM - fm) < WGM ? (nM - fm) : WGM;
;         u.pm = fm + ((wgid % nig) % gsz); u.pn = (wgid % nig) / gsz; u.z = 0; return true;
.LBB0_2049:
	v_readlane_b32 s6, v254, 2
	s_add_i32 s40, s40, 1
	s_mul_i32 s4, s40, s43
	s_waitcnt lgkmcnt(0)
	s_mul_hi_u32 s5, s40, s6
	s_add_i32 s5, s5, s4
	s_mul_i32 s4, s40, s6
	s_add_u32 s4, s4, s74
	s_addc_u32 s5, s5, s44
	v_cmp_gt_i64_e32 vcc, s[4:5], v[168:169]
	v_cmp_lt_i64_e64 s[6:7], s[4:5], v[166:167]
	s_cbranch_vccnz .LBB0_2055
	s_ashr_i32 s5, s4, 31
	s_lshr_b32 s5, s5, 29
	s_add_i32 s22, s4, s5
	s_and_b32 s5, s22, -8
	s_sub_i32 s23, s4, s5
	s_cmp_gt_i32 s23, -1
	s_mov_b64 s[4:5], -1
	s_cbranch_scc0 .LBB0_2052
	s_lshl_b32 s28, s23, 7
	s_mov_b64 s[4:5], 0

;     __host__ __device__ bool next(int i, Unit& u) const { const bool ok = StaticOrder::next(i >> 1, u); u.z = i & 1; return ok; }
;     __host__ __device__ bool next(int i, Unit& u) const {
;         const long L = (long)i * G + c; if (L >= nwg) return false;
;         int wgid = (int)L; { const int q = nwg / NXCD, r = nwg % NXCD, xcd = wgid % NXCD, off = wgid / NXCD; wgid = (xcd < r ? xcd * (q + 1) : r * (q + 1) + (xcd - r) * q) + off; }
;         const int nig = WGM * nN, gid = wgid / nig, fm = gid * WGM, gsz = (nM - fm) < WGM ? (nM - fm) : WGM;
;         u.pm = fm + ((wgid % nig) % gsz); u.pn = (wgid % nig) / gsz; u.z = 0; return true;
.LBB0_2093:
	v_readlane_b32 s16, v254, 13
	v_readlane_b32 s17, v254, 14
	v_readlane_b32 s13, v254, 2
	s_add_i32 s50, s50, 1
	s_mul_i32 s0, s50, s53
	s_waitcnt lgkmcnt(0)
	s_mul_hi_u32 s1, s50, s13
	s_add_i32 s1, s1, s0
	s_mul_i32 s0, s50, s13
	s_add_u32 s16, s0, s74
	s_addc_u32 s17, s1, s33
	v_cmp_gt_i64_e32 vcc, s[16:17], v[140:141]
	v_cmp_lt_i64_e64 s[0:1], s[16:17], v[138:139]
	s_cbranch_vccnz .LBB0_2099
	s_ashr_i32 s12, s16, 31
	s_lshr_b32 s12, s12, 29
	s_add_i32 s14, s16, s12
	s_and_b32 s12, s14, -8
	s_sub_i32 s15, s16, s12
	s_cmp_gt_i32 s15, -1
	s_mov_b64 s[12:13], -1
	s_cbranch_scc0 .LBB0_2096
	s_lshl_b32 s16, s15, 7
	s_mov_b64 s[12:13], 0
